# GEMM loops: src1 (activation fragment) held for 4 consecutive MFMAs, accumulator forwarding only at run joins
# baseline (speedup 1.0000x reference)
.LBB0_178:
	s_add_u32 s26, s22, 0xfffc0080
	s_addc_u32 s27, s23, -1
	s_add_i32 s34, 0, 0x10000
	s_cmp_eq_u32 s59, 12
	s_cselect_b32 s31, s9, s27
	s_cselect_b32 s30, s15, s26
	s_cselect_b32 s27, s13, s58
	s_cselect_b32 s26, s56, s57
	s_add_i32 s35, 0, 0x14000
	v_add_u32_e32 v140, s34, v195
	v_add_u32_e32 v166, s35, v195
	ds_read_b128 v[128:131], v140
	ds_read_b128 v[132:135], v140 offset:1024
	ds_read_b128 v[136:139], v140 offset:2048
	ds_read_b128 v[140:143], v140 offset:3072
	ds_read_b128 v[144:147], v166
	ds_read_b128 v[148:151], v166 offset:1024
	ds_read_b128 v[180:183], v166 offset:2048
	ds_read_b128 v[184:187], v166 offset:3072
	s_add_i32 m0, s49, 0xc000
	ds_read_b128 v[188:191], v200
	ds_read_b128 v[202:205], v200 offset:1024
	ds_read_b128 v[206:209], v200 offset:2048
	ds_read_b128 v[210:213], v200 offset:3072
	ds_read_b128 v[228:231], v200 offset:4096
	ds_read_b128 v[232:235], v200 offset:5120
	ds_read_b128 v[236:239], v200 offset:6144
	ds_read_b128 v[240:243], v200 offset:7168
	global_load_lds_dwordx4 v160, s[22:23]
	s_add_i32 m0, s49, 0xe000
	s_nop 0
	global_load_lds_dwordx4 v162, s[22:23]
	s_waitcnt vmcnt(8)
	s_waitcnt lgkmcnt(0)
	s_barrier
	s_setprio 1
	s_waitcnt lgkmcnt(0)
	v_mfma_f32_16x16x32_bf16 v[124:127], v[128:131], v[188:191], v[124:127]
	v_mfma_f32_16x16x32_bf16 v[120:123], v[136:139], v[188:191], v[120:123]
	v_mfma_f32_16x16x32_bf16 v[116:119], v[144:147], v[188:191], v[116:119]
	v_mfma_f32_16x16x32_bf16 v[108:111], v[180:183], v[188:191], v[108:111]
	v_mfma_f32_16x16x32_bf16 v[108:111], v[184:187], v[202:205], v[108:111]
	v_mfma_f32_16x16x32_bf16 v[116:119], v[148:151], v[202:205], v[116:119]
	v_mfma_f32_16x16x32_bf16 v[120:123], v[140:143], v[202:205], v[120:123]
	v_mfma_f32_16x16x32_bf16 v[124:127], v[132:135], v[202:205], v[124:127]
	v_mfma_f32_16x16x32_bf16 v[112:115], v[132:135], v[210:213], v[112:115]
	v_mfma_f32_16x16x32_bf16 v[104:107], v[140:143], v[210:213], v[104:107]
	v_mfma_f32_16x16x32_bf16 v[100:103], v[148:151], v[210:213], v[100:103]
	v_mfma_f32_16x16x32_bf16 v[92:95], v[184:187], v[210:213], v[92:95]
	v_mfma_f32_16x16x32_bf16 v[92:95], v[180:183], v[206:209], v[92:95]
	v_mfma_f32_16x16x32_bf16 v[100:103], v[144:147], v[206:209], v[100:103]
	v_mfma_f32_16x16x32_bf16 v[104:107], v[136:139], v[206:209], v[104:107]
	v_mfma_f32_16x16x32_bf16 v[112:115], v[128:131], v[206:209], v[112:115]
	v_mfma_f32_16x16x32_bf16 v[96:99], v[128:131], v[228:231], v[96:99]
	v_mfma_f32_16x16x32_bf16 v[88:91], v[136:139], v[228:231], v[88:91]
	v_mfma_f32_16x16x32_bf16 v[84:87], v[144:147], v[228:231], v[84:87]
	v_mfma_f32_16x16x32_bf16 v[76:79], v[180:183], v[228:231], v[76:79]
	v_mfma_f32_16x16x32_bf16 v[76:79], v[184:187], v[232:235], v[76:79]
	v_mfma_f32_16x16x32_bf16 v[84:87], v[148:151], v[232:235], v[84:87]
	v_mfma_f32_16x16x32_bf16 v[88:91], v[140:143], v[232:235], v[88:91]
	v_mfma_f32_16x16x32_bf16 v[96:99], v[132:135], v[232:235], v[96:99]
	v_mfma_f32_16x16x32_bf16 v[80:83], v[132:135], v[240:243], v[80:83]
	v_mfma_f32_16x16x32_bf16 v[72:75], v[140:143], v[240:243], v[72:75]
	v_mfma_f32_16x16x32_bf16 v[68:71], v[148:151], v[240:243], v[68:71]
	v_mfma_f32_16x16x32_bf16 v[64:67], v[184:187], v[240:243], v[64:67]
	v_mfma_f32_16x16x32_bf16 v[64:67], v[180:183], v[236:239], v[64:67]
	v_mfma_f32_16x16x32_bf16 v[68:71], v[144:147], v[236:239], v[68:71]
	v_mfma_f32_16x16x32_bf16 v[72:75], v[136:139], v[236:239], v[72:75]
	v_mfma_f32_16x16x32_bf16 v[80:83], v[128:131], v[236:239], v[80:83]
	s_setprio 0
	s_barrier
	s_add_i32 s34, s34, s45
	s_add_u32 s98, s26, s20
	s_addc_u32 s99, s27, s21
	s_mov_b32 m0, s34
	ds_read_b128 v[188:191], v200 offset:16384
	ds_read_b128 v[202:205], v200 offset:17408
	ds_read_b128 v[206:209], v200 offset:18432
	ds_read_b128 v[210:213], v200 offset:19456
	ds_read_b128 v[228:231], v200 offset:20480
	ds_read_b128 v[232:235], v200 offset:21504
	ds_read_b128 v[236:239], v200 offset:22528
	ds_read_b128 v[240:243], v200 offset:23552
	global_load_lds_dwordx4 v168, s[26:27]
	s_add_i32 m0, s34, 0x2000
	s_add_u32 s36, s26, 0x40000
	s_addc_u32 s37, s27, 0
	s_add_i32 s34, s35, s45
	global_load_lds_dwordx4 v152, s[26:27]
	s_mov_b32 m0, s34
	s_nop 0
	global_load_lds_dwordx4 v168, s[36:37]
	s_add_i32 m0, s34, 0x2000
	s_nop 0
	global_load_lds_dwordx4 v152, s[36:37]
	s_add_u32 s100, s30, s20
	s_addc_u32 s101, s31, s21
	s_mov_b32 m0, s49
	s_nop 0
	global_load_lds_dwordx4 v156, s[30:31]
	s_mov_b32 m0, s50
	s_nop 0
	global_load_lds_dwordx4 v154, s[30:31]
	s_waitcnt vmcnt(8)
	s_waitcnt lgkmcnt(0)
	s_barrier
	s_setprio 1
	s_waitcnt lgkmcnt(0)
	v_mfma_f32_16x16x32_bf16 v[60:63], v[128:131], v[188:191], v[60:63]
	v_mfma_f32_16x16x32_bf16 v[56:59], v[136:139], v[188:191], v[56:59]
	v_mfma_f32_16x16x32_bf16 v[52:55], v[144:147], v[188:191], v[52:55]
	v_mfma_f32_16x16x32_bf16 v[44:47], v[180:183], v[188:191], v[44:47]
	v_mfma_f32_16x16x32_bf16 v[44:47], v[184:187], v[202:205], v[44:47]
	v_mfma_f32_16x16x32_bf16 v[52:55], v[148:151], v[202:205], v[52:55]
	v_mfma_f32_16x16x32_bf16 v[56:59], v[140:143], v[202:205], v[56:59]
	v_mfma_f32_16x16x32_bf16 v[60:63], v[132:135], v[202:205], v[60:63]
	v_mfma_f32_16x16x32_bf16 v[48:51], v[132:135], v[210:213], v[48:51]
	v_mfma_f32_16x16x32_bf16 v[40:43], v[140:143], v[210:213], v[40:43]
	v_mfma_f32_16x16x32_bf16 v[36:39], v[148:151], v[210:213], v[36:39]
	v_mfma_f32_16x16x32_bf16 v[28:31], v[184:187], v[210:213], v[28:31]
	v_mfma_f32_16x16x32_bf16 v[28:31], v[180:183], v[206:209], v[28:31]
	v_mfma_f32_16x16x32_bf16 v[36:39], v[144:147], v[206:209], v[36:39]
	v_mfma_f32_16x16x32_bf16 v[40:43], v[136:139], v[206:209], v[40:43]
	v_mfma_f32_16x16x32_bf16 v[48:51], v[128:131], v[206:209], v[48:51]
	v_mfma_f32_16x16x32_bf16 v[32:35], v[128:131], v[228:231], v[32:35]
	v_mfma_f32_16x16x32_bf16 v[24:27], v[136:139], v[228:231], v[24:27]
	v_mfma_f32_16x16x32_bf16 v[20:23], v[144:147], v[228:231], v[20:23]
	v_mfma_f32_16x16x32_bf16 v[12:15], v[180:183], v[228:231], v[12:15]
	v_mfma_f32_16x16x32_bf16 v[12:15], v[184:187], v[232:235], v[12:15]
	v_mfma_f32_16x16x32_bf16 v[20:23], v[148:151], v[232:235], v[20:23]
	v_mfma_f32_16x16x32_bf16 v[24:27], v[140:143], v[232:235], v[24:27]
	v_mfma_f32_16x16x32_bf16 v[32:35], v[132:135], v[232:235], v[32:35]
	v_mfma_f32_16x16x32_bf16 v[16:19], v[132:135], v[240:243], v[16:19]
	v_mfma_f32_16x16x32_bf16 v[8:11], v[140:143], v[240:243], v[8:11]
	v_mfma_f32_16x16x32_bf16 v[4:7], v[148:151], v[240:243], v[4:7]
	v_mfma_f32_16x16x32_bf16 v[0:3], v[184:187], v[240:243], v[0:3]
	v_mfma_f32_16x16x32_bf16 v[0:3], v[180:183], v[236:239], v[0:3]
	v_mfma_f32_16x16x32_bf16 v[4:7], v[144:147], v[236:239], v[4:7]
	v_mfma_f32_16x16x32_bf16 v[8:11], v[136:139], v[236:239], v[8:11]
	v_mfma_f32_16x16x32_bf16 v[16:19], v[128:131], v[236:239], v[16:19]
	s_setprio 0
	s_barrier
	s_add_i32 s34, 0, 0x18000
	s_add_i32 s35, 0, 0x1c000
	v_add_u32_e32 v140, s34, v195
	v_add_u32_e32 v184, s35, v195
	ds_read_b128 v[128:131], v140
	ds_read_b128 v[132:135], v140 offset:1024
	ds_read_b128 v[136:139], v140 offset:2048
	ds_read_b128 v[140:143], v140 offset:3072
	ds_read_b128 v[144:147], v184
	ds_read_b128 v[148:151], v184 offset:1024
	ds_read_b128 v[180:183], v184 offset:2048
	ds_read_b128 v[184:187], v184 offset:3072
	s_add_u32 s30, s30, 0x40000
	s_addc_u32 s31, s31, 0
	s_mov_b32 m0, s51
	ds_read_b128 v[188:191], v200 offset:32768
	ds_read_b128 v[202:205], v200 offset:33792
	ds_read_b128 v[206:209], v200 offset:34816
	ds_read_b128 v[210:213], v200 offset:35840
	ds_read_b128 v[228:231], v200 offset:36864
	ds_read_b128 v[232:235], v200 offset:37888
	ds_read_b128 v[236:239], v200 offset:38912
	ds_read_b128 v[240:243], v200 offset:39936
	global_load_lds_dwordx4 v156, s[30:31]
	s_mov_b32 m0, s52
	s_nop 0
	global_load_lds_dwordx4 v154, s[30:31]
	s_waitcnt vmcnt(8)
	s_waitcnt lgkmcnt(0)
	s_barrier
	s_setprio 1
	s_waitcnt lgkmcnt(0)
	v_mfma_f32_16x16x32_bf16 v[124:127], v[128:131], v[188:191], v[124:127]
	v_mfma_f32_16x16x32_bf16 v[120:123], v[136:139], v[188:191], v[120:123]
	v_mfma_f32_16x16x32_bf16 v[116:119], v[144:147], v[188:191], v[116:119]
	v_mfma_f32_16x16x32_bf16 v[108:111], v[180:183], v[188:191], v[108:111]
	v_mfma_f32_16x16x32_bf16 v[108:111], v[184:187], v[202:205], v[108:111]
	v_mfma_f32_16x16x32_bf16 v[116:119], v[148:151], v[202:205], v[116:119]
	v_mfma_f32_16x16x32_bf16 v[120:123], v[140:143], v[202:205], v[120:123]
	v_mfma_f32_16x16x32_bf16 v[124:127], v[132:135], v[202:205], v[124:127]
	v_mfma_f32_16x16x32_bf16 v[112:115], v[132:135], v[210:213], v[112:115]
	v_mfma_f32_16x16x32_bf16 v[104:107], v[140:143], v[210:213], v[104:107]
	v_mfma_f32_16x16x32_bf16 v[100:103], v[148:151], v[210:213], v[100:103]
	v_mfma_f32_16x16x32_bf16 v[92:95], v[184:187], v[210:213], v[92:95]
	v_mfma_f32_16x16x32_bf16 v[92:95], v[180:183], v[206:209], v[92:95]
	v_mfma_f32_16x16x32_bf16 v[100:103], v[144:147], v[206:209], v[100:103]
	v_mfma_f32_16x16x32_bf16 v[104:107], v[136:139], v[206:209], v[104:107]
	v_mfma_f32_16x16x32_bf16 v[112:115], v[128:131], v[206:209], v[112:115]
	v_mfma_f32_16x16x32_bf16 v[96:99], v[128:131], v[228:231], v[96:99]
	v_mfma_f32_16x16x32_bf16 v[88:91], v[136:139], v[228:231], v[88:91]
	v_mfma_f32_16x16x32_bf16 v[84:87], v[144:147], v[228:231], v[84:87]
	v_mfma_f32_16x16x32_bf16 v[76:79], v[180:183], v[228:231], v[76:79]
	v_mfma_f32_16x16x32_bf16 v[76:79], v[184:187], v[232:235], v[76:79]
	v_mfma_f32_16x16x32_bf16 v[84:87], v[148:151], v[232:235], v[84:87]
	v_mfma_f32_16x16x32_bf16 v[88:91], v[140:143], v[232:235], v[88:91]
	v_mfma_f32_16x16x32_bf16 v[96:99], v[132:135], v[232:235], v[96:99]
	v_mfma_f32_16x16x32_bf16 v[80:83], v[132:135], v[240:243], v[80:83]
	v_mfma_f32_16x16x32_bf16 v[72:75], v[140:143], v[240:243], v[72:75]
	v_mfma_f32_16x16x32_bf16 v[68:71], v[148:151], v[240:243], v[68:71]
	v_mfma_f32_16x16x32_bf16 v[64:67], v[184:187], v[240:243], v[64:67]
	v_mfma_f32_16x16x32_bf16 v[64:67], v[180:183], v[236:239], v[64:67]
	v_mfma_f32_16x16x32_bf16 v[68:71], v[144:147], v[236:239], v[68:71]
	v_mfma_f32_16x16x32_bf16 v[72:75], v[136:139], v[236:239], v[72:75]
	v_mfma_f32_16x16x32_bf16 v[80:83], v[128:131], v[236:239], v[80:83]
	s_setprio 0
	s_barrier
	s_add_i32 s30, s34, s45
	s_mov_b32 m0, s30
	ds_read_b128 v[188:191], v200 offset:49152
	ds_read_b128 v[202:205], v200 offset:50176
	ds_read_b128 v[206:209], v200 offset:51200
	ds_read_b128 v[210:213], v200 offset:52224
	ds_read_b128 v[228:231], v200 offset:53248
	ds_read_b128 v[232:235], v200 offset:54272
	ds_read_b128 v[236:239], v200 offset:55296
	ds_read_b128 v[240:243], v200 offset:56320
	global_load_lds_dwordx4 v168, s[98:99]
	s_add_i32 m0, s30, 0x2000
	s_add_u32 s26, s26, 0x40080
	s_addc_u32 s27, s27, 0
	s_add_i32 s30, s35, s45
	global_load_lds_dwordx4 v152, s[98:99]
	s_mov_b32 m0, s30
	s_nop 0
	global_load_lds_dwordx4 v168, s[26:27]
	s_add_i32 m0, s30, 0x2000
	s_nop 0
	global_load_lds_dwordx4 v152, s[26:27]
	s_mov_b32 m0, s24
	s_nop 0
	global_load_lds_dwordx4 v156, s[100:101]
	s_mov_b32 m0, s53
	s_nop 0
	global_load_lds_dwordx4 v154, s[100:101]
	s_waitcnt vmcnt(8)
	s_waitcnt lgkmcnt(0)
	s_barrier
	s_setprio 1
	s_waitcnt lgkmcnt(0)
	v_mfma_f32_16x16x32_bf16 v[60:63], v[128:131], v[188:191], v[60:63]
	v_mfma_f32_16x16x32_bf16 v[56:59], v[136:139], v[188:191], v[56:59]
	v_mfma_f32_16x16x32_bf16 v[52:55], v[144:147], v[188:191], v[52:55]
	v_mfma_f32_16x16x32_bf16 v[44:47], v[180:183], v[188:191], v[44:47]
	v_mfma_f32_16x16x32_bf16 v[44:47], v[184:187], v[202:205], v[44:47]
	v_mfma_f32_16x16x32_bf16 v[52:55], v[148:151], v[202:205], v[52:55]
	v_mfma_f32_16x16x32_bf16 v[56:59], v[140:143], v[202:205], v[56:59]
	v_mfma_f32_16x16x32_bf16 v[60:63], v[132:135], v[202:205], v[60:63]
	v_mfma_f32_16x16x32_bf16 v[48:51], v[132:135], v[210:213], v[48:51]
	v_mfma_f32_16x16x32_bf16 v[40:43], v[140:143], v[210:213], v[40:43]
	v_mfma_f32_16x16x32_bf16 v[36:39], v[148:151], v[210:213], v[36:39]
	v_mfma_f32_16x16x32_bf16 v[28:31], v[184:187], v[210:213], v[28:31]
	v_mfma_f32_16x16x32_bf16 v[28:31], v[180:183], v[206:209], v[28:31]
	v_mfma_f32_16x16x32_bf16 v[36:39], v[144:147], v[206:209], v[36:39]
	v_mfma_f32_16x16x32_bf16 v[40:43], v[136:139], v[206:209], v[40:43]
	v_mfma_f32_16x16x32_bf16 v[48:51], v[128:131], v[206:209], v[48:51]
	v_mfma_f32_16x16x32_bf16 v[32:35], v[128:131], v[228:231], v[32:35]
	v_mfma_f32_16x16x32_bf16 v[24:27], v[136:139], v[228:231], v[24:27]
	v_mfma_f32_16x16x32_bf16 v[20:23], v[144:147], v[228:231], v[20:23]
	v_mfma_f32_16x16x32_bf16 v[12:15], v[180:183], v[228:231], v[12:15]
	v_mfma_f32_16x16x32_bf16 v[12:15], v[184:187], v[232:235], v[12:15]
	v_mfma_f32_16x16x32_bf16 v[20:23], v[148:151], v[232:235], v[20:23]
	v_mfma_f32_16x16x32_bf16 v[24:27], v[140:143], v[232:235], v[24:27]
	v_mfma_f32_16x16x32_bf16 v[32:35], v[132:135], v[232:235], v[32:35]
	v_mfma_f32_16x16x32_bf16 v[16:19], v[132:135], v[240:243], v[16:19]
	v_mfma_f32_16x16x32_bf16 v[8:11], v[140:143], v[240:243], v[8:11]
	v_mfma_f32_16x16x32_bf16 v[4:7], v[148:151], v[240:243], v[4:7]
	v_mfma_f32_16x16x32_bf16 v[0:3], v[184:187], v[240:243], v[0:3]
	v_mfma_f32_16x16x32_bf16 v[0:3], v[180:183], v[236:239], v[0:3]
	v_mfma_f32_16x16x32_bf16 v[4:7], v[144:147], v[236:239], v[4:7]
	v_mfma_f32_16x16x32_bf16 v[8:11], v[136:139], v[236:239], v[8:11]
	v_mfma_f32_16x16x32_bf16 v[16:19], v[128:131], v[236:239], v[16:19]
	s_setprio 0
	s_barrier
	s_add_i32 s59, s59, 2
	s_add_u32 s22, s22, 0x100
	s_addc_u32 s23, s23, 0
	s_add_u32 s57, s57, 0x100
	s_addc_u32 s58, s58, 0
	s_cmp_gt_u32 s59, 13
	s_cbranch_scc0 .LBB0_178
	s_and_b64 vcc, exec, s[10:11]
	s_cbranch_vccz .LBB0_181
	s_barrier

.LBB0_776:
	s_add_u32 s26, s22, 0xfffc0080
	s_addc_u32 s27, s23, -1
	s_add_i32 s36, 0, 0x10000
	s_cmp_eq_u32 s55, 12
	s_cselect_b32 s31, s15, s27
	s_cselect_b32 s30, s51, s26
	s_cselect_b32 s27, s13, s54
	s_cselect_b32 s26, s52, s53
	s_add_i32 s56, 0, 0x14000
	v_add_u32_e32 v140, s36, v204
	v_add_u32_e32 v156, s56, v204
	ds_read_b128 v[128:131], v140
	ds_read_b128 v[132:135], v140 offset:1024
	ds_read_b128 v[136:139], v140 offset:2048
	ds_read_b128 v[140:143], v140 offset:3072
	ds_read_b128 v[144:147], v156
	ds_read_b128 v[148:151], v156 offset:1024
	ds_read_b128 v[152:155], v156 offset:2048
	ds_read_b128 v[156:159], v156 offset:3072
	s_add_i32 m0, s42, 0xc000
	ds_read_b128 v[182:185], v206
	ds_read_b128 v[186:189], v206 offset:1024
	ds_read_b128 v[190:193], v206 offset:2048
	ds_read_b128 v[194:197], v206 offset:3072
	ds_read_b128 v[198:201], v206 offset:4096
	ds_read_b128 v[208:211], v206 offset:5120
	ds_read_b128 v[212:215], v206 offset:6144
	ds_read_b128 v[228:231], v206 offset:7168
	global_load_lds_dwordx4 v166, s[22:23]
	s_add_i32 m0, s42, 0xe000
	s_nop 0
	global_load_lds_dwordx4 v180, s[22:23]
	s_waitcnt vmcnt(8)
	s_waitcnt lgkmcnt(0)
	s_barrier
	s_setprio 1
	s_waitcnt lgkmcnt(0)
	v_mfma_f32_16x16x32_bf16 v[124:127], v[128:131], v[182:185], v[124:127]
	v_mfma_f32_16x16x32_bf16 v[120:123], v[136:139], v[182:185], v[120:123]
	v_mfma_f32_16x16x32_bf16 v[116:119], v[144:147], v[182:185], v[116:119]
	v_mfma_f32_16x16x32_bf16 v[112:115], v[152:155], v[182:185], v[112:115]
	v_mfma_f32_16x16x32_bf16 v[112:115], v[156:159], v[186:189], v[112:115]
	v_mfma_f32_16x16x32_bf16 v[116:119], v[148:151], v[186:189], v[116:119]
	v_mfma_f32_16x16x32_bf16 v[120:123], v[140:143], v[186:189], v[120:123]
	v_mfma_f32_16x16x32_bf16 v[124:127], v[132:135], v[186:189], v[124:127]
	v_mfma_f32_16x16x32_bf16 v[108:111], v[132:135], v[194:197], v[108:111]
	v_mfma_f32_16x16x32_bf16 v[104:107], v[140:143], v[194:197], v[104:107]
	v_mfma_f32_16x16x32_bf16 v[100:103], v[148:151], v[194:197], v[100:103]
	v_mfma_f32_16x16x32_bf16 v[96:99], v[156:159], v[194:197], v[96:99]
	v_mfma_f32_16x16x32_bf16 v[96:99], v[152:155], v[190:193], v[96:99]
	v_mfma_f32_16x16x32_bf16 v[100:103], v[144:147], v[190:193], v[100:103]
	v_mfma_f32_16x16x32_bf16 v[104:107], v[136:139], v[190:193], v[104:107]
	v_mfma_f32_16x16x32_bf16 v[108:111], v[128:131], v[190:193], v[108:111]
	v_mfma_f32_16x16x32_bf16 v[92:95], v[128:131], v[198:201], v[92:95]
	v_mfma_f32_16x16x32_bf16 v[88:91], v[136:139], v[198:201], v[88:91]
	v_mfma_f32_16x16x32_bf16 v[84:87], v[144:147], v[198:201], v[84:87]
	v_mfma_f32_16x16x32_bf16 v[80:83], v[152:155], v[198:201], v[80:83]
	v_mfma_f32_16x16x32_bf16 v[80:83], v[156:159], v[208:211], v[80:83]
	v_mfma_f32_16x16x32_bf16 v[84:87], v[148:151], v[208:211], v[84:87]
	v_mfma_f32_16x16x32_bf16 v[88:91], v[140:143], v[208:211], v[88:91]
	v_mfma_f32_16x16x32_bf16 v[92:95], v[132:135], v[208:211], v[92:95]
	v_mfma_f32_16x16x32_bf16 v[76:79], v[132:135], v[228:231], v[76:79]
	v_mfma_f32_16x16x32_bf16 v[72:75], v[140:143], v[228:231], v[72:75]
	v_mfma_f32_16x16x32_bf16 v[68:71], v[148:151], v[228:231], v[68:71]
	v_mfma_f32_16x16x32_bf16 v[64:67], v[156:159], v[228:231], v[64:67]
	v_mfma_f32_16x16x32_bf16 v[64:67], v[152:155], v[212:215], v[64:67]
	v_mfma_f32_16x16x32_bf16 v[68:71], v[144:147], v[212:215], v[68:71]
	v_mfma_f32_16x16x32_bf16 v[72:75], v[136:139], v[212:215], v[72:75]
	v_mfma_f32_16x16x32_bf16 v[76:79], v[128:131], v[212:215], v[76:79]
	s_setprio 0
	s_barrier
	s_add_i32 s36, s36, s35
	s_add_u32 s98, s26, s20
	s_addc_u32 s99, s27, s21
	s_mov_b32 m0, s36
	ds_read_b128 v[182:185], v206 offset:16384
	ds_read_b128 v[186:189], v206 offset:17408
	ds_read_b128 v[190:193], v206 offset:18432
	ds_read_b128 v[194:197], v206 offset:19456
	ds_read_b128 v[198:201], v206 offset:20480
	ds_read_b128 v[208:211], v206 offset:21504
	ds_read_b128 v[212:215], v206 offset:22528
	ds_read_b128 v[228:231], v206 offset:23552
	global_load_lds_dwordx4 v168, s[26:27]
	s_add_i32 m0, s36, 0x2000
	s_add_u32 s36, s26, 0x40000
	s_addc_u32 s37, s27, 0
	s_add_i32 s56, s56, s35
	global_load_lds_dwordx4 v160, s[26:27]
	s_mov_b32 m0, s56
	s_nop 0
	global_load_lds_dwordx4 v168, s[36:37]
	s_add_i32 m0, s56, 0x2000
	s_nop 0
	global_load_lds_dwordx4 v160, s[36:37]
	s_add_u32 s100, s30, s20
	s_addc_u32 s101, s31, s21
	s_mov_b32 m0, s42
	s_nop 0
	global_load_lds_dwordx4 v164, s[30:31]
	s_mov_b32 m0, s43
	s_nop 0
	global_load_lds_dwordx4 v162, s[30:31]
	s_waitcnt vmcnt(8)
	s_waitcnt lgkmcnt(0)
	s_barrier
	s_setprio 1
	s_waitcnt lgkmcnt(0)
	v_mfma_f32_16x16x32_bf16 v[60:63], v[128:131], v[182:185], v[60:63]
	v_mfma_f32_16x16x32_bf16 v[56:59], v[136:139], v[182:185], v[56:59]
	v_mfma_f32_16x16x32_bf16 v[52:55], v[144:147], v[182:185], v[52:55]
	v_mfma_f32_16x16x32_bf16 v[48:51], v[152:155], v[182:185], v[48:51]
	v_mfma_f32_16x16x32_bf16 v[48:51], v[156:159], v[186:189], v[48:51]
	v_mfma_f32_16x16x32_bf16 v[52:55], v[148:151], v[186:189], v[52:55]
	v_mfma_f32_16x16x32_bf16 v[56:59], v[140:143], v[186:189], v[56:59]
	v_mfma_f32_16x16x32_bf16 v[60:63], v[132:135], v[186:189], v[60:63]
	v_mfma_f32_16x16x32_bf16 v[44:47], v[132:135], v[194:197], v[44:47]
	v_mfma_f32_16x16x32_bf16 v[40:43], v[140:143], v[194:197], v[40:43]
	v_mfma_f32_16x16x32_bf16 v[36:39], v[148:151], v[194:197], v[36:39]
	v_mfma_f32_16x16x32_bf16 v[32:35], v[156:159], v[194:197], v[32:35]
	v_mfma_f32_16x16x32_bf16 v[32:35], v[152:155], v[190:193], v[32:35]
	v_mfma_f32_16x16x32_bf16 v[36:39], v[144:147], v[190:193], v[36:39]
	v_mfma_f32_16x16x32_bf16 v[40:43], v[136:139], v[190:193], v[40:43]
	v_mfma_f32_16x16x32_bf16 v[44:47], v[128:131], v[190:193], v[44:47]
	v_mfma_f32_16x16x32_bf16 v[28:31], v[128:131], v[198:201], v[28:31]
	v_mfma_f32_16x16x32_bf16 v[24:27], v[136:139], v[198:201], v[24:27]
	v_mfma_f32_16x16x32_bf16 v[20:23], v[144:147], v[198:201], v[20:23]
	v_mfma_f32_16x16x32_bf16 v[16:19], v[152:155], v[198:201], v[16:19]
	v_mfma_f32_16x16x32_bf16 v[16:19], v[156:159], v[208:211], v[16:19]
	v_mfma_f32_16x16x32_bf16 v[20:23], v[148:151], v[208:211], v[20:23]
	v_mfma_f32_16x16x32_bf16 v[24:27], v[140:143], v[208:211], v[24:27]
	v_mfma_f32_16x16x32_bf16 v[28:31], v[132:135], v[208:211], v[28:31]
	v_mfma_f32_16x16x32_bf16 v[12:15], v[132:135], v[228:231], v[12:15]
	v_mfma_f32_16x16x32_bf16 v[8:11], v[140:143], v[228:231], v[8:11]
	v_mfma_f32_16x16x32_bf16 v[4:7], v[148:151], v[228:231], v[4:7]
	v_mfma_f32_16x16x32_bf16 v[0:3], v[156:159], v[228:231], v[0:3]
	v_mfma_f32_16x16x32_bf16 v[0:3], v[152:155], v[212:215], v[0:3]
	v_mfma_f32_16x16x32_bf16 v[4:7], v[144:147], v[212:215], v[4:7]
	v_mfma_f32_16x16x32_bf16 v[8:11], v[136:139], v[212:215], v[8:11]
	v_mfma_f32_16x16x32_bf16 v[12:15], v[128:131], v[212:215], v[12:15]
	s_setprio 0
	s_barrier
	s_add_i32 s36, 0, 0x18000
	s_add_i32 s37, 0, 0x1c000
	v_add_u32_e32 v140, s36, v204
	v_add_u32_e32 v156, s37, v204
	ds_read_b128 v[128:131], v140
	ds_read_b128 v[132:135], v140 offset:1024
	ds_read_b128 v[136:139], v140 offset:2048
	ds_read_b128 v[140:143], v140 offset:3072
	ds_read_b128 v[144:147], v156
	ds_read_b128 v[148:151], v156 offset:1024
	ds_read_b128 v[152:155], v156 offset:2048
	ds_read_b128 v[156:159], v156 offset:3072
	s_add_u32 s30, s30, 0x40000
	s_addc_u32 s31, s31, 0
	s_mov_b32 m0, s44
	ds_read_b128 v[182:185], v206 offset:32768
	ds_read_b128 v[186:189], v206 offset:33792
	ds_read_b128 v[190:193], v206 offset:34816
	ds_read_b128 v[194:197], v206 offset:35840
	ds_read_b128 v[198:201], v206 offset:36864
	ds_read_b128 v[208:211], v206 offset:37888
	ds_read_b128 v[212:215], v206 offset:38912
	ds_read_b128 v[228:231], v206 offset:39936
	global_load_lds_dwordx4 v164, s[30:31]
	s_mov_b32 m0, s45
	s_nop 0
	global_load_lds_dwordx4 v162, s[30:31]
	s_waitcnt vmcnt(8)
	s_waitcnt lgkmcnt(0)
	s_barrier
	s_setprio 1
	s_waitcnt lgkmcnt(0)
	v_mfma_f32_16x16x32_bf16 v[124:127], v[128:131], v[182:185], v[124:127]
	v_mfma_f32_16x16x32_bf16 v[120:123], v[136:139], v[182:185], v[120:123]
	v_mfma_f32_16x16x32_bf16 v[116:119], v[144:147], v[182:185], v[116:119]
	v_mfma_f32_16x16x32_bf16 v[112:115], v[152:155], v[182:185], v[112:115]
	v_mfma_f32_16x16x32_bf16 v[112:115], v[156:159], v[186:189], v[112:115]
	v_mfma_f32_16x16x32_bf16 v[116:119], v[148:151], v[186:189], v[116:119]
	v_mfma_f32_16x16x32_bf16 v[120:123], v[140:143], v[186:189], v[120:123]
	v_mfma_f32_16x16x32_bf16 v[124:127], v[132:135], v[186:189], v[124:127]
	v_mfma_f32_16x16x32_bf16 v[108:111], v[132:135], v[194:197], v[108:111]
	v_mfma_f32_16x16x32_bf16 v[104:107], v[140:143], v[194:197], v[104:107]
	v_mfma_f32_16x16x32_bf16 v[100:103], v[148:151], v[194:197], v[100:103]
	v_mfma_f32_16x16x32_bf16 v[96:99], v[156:159], v[194:197], v[96:99]
	v_mfma_f32_16x16x32_bf16 v[96:99], v[152:155], v[190:193], v[96:99]
	v_mfma_f32_16x16x32_bf16 v[100:103], v[144:147], v[190:193], v[100:103]
	v_mfma_f32_16x16x32_bf16 v[104:107], v[136:139], v[190:193], v[104:107]
	v_mfma_f32_16x16x32_bf16 v[108:111], v[128:131], v[190:193], v[108:111]
	v_mfma_f32_16x16x32_bf16 v[92:95], v[128:131], v[198:201], v[92:95]
	v_mfma_f32_16x16x32_bf16 v[88:91], v[136:139], v[198:201], v[88:91]
	v_mfma_f32_16x16x32_bf16 v[84:87], v[144:147], v[198:201], v[84:87]
	v_mfma_f32_16x16x32_bf16 v[80:83], v[152:155], v[198:201], v[80:83]
	v_mfma_f32_16x16x32_bf16 v[80:83], v[156:159], v[208:211], v[80:83]
	v_mfma_f32_16x16x32_bf16 v[84:87], v[148:151], v[208:211], v[84:87]
	v_mfma_f32_16x16x32_bf16 v[88:91], v[140:143], v[208:211], v[88:91]
	v_mfma_f32_16x16x32_bf16 v[92:95], v[132:135], v[208:211], v[92:95]
	v_mfma_f32_16x16x32_bf16 v[76:79], v[132:135], v[228:231], v[76:79]
	v_mfma_f32_16x16x32_bf16 v[72:75], v[140:143], v[228:231], v[72:75]
	v_mfma_f32_16x16x32_bf16 v[68:71], v[148:151], v[228:231], v[68:71]
	v_mfma_f32_16x16x32_bf16 v[64:67], v[156:159], v[228:231], v[64:67]
	v_mfma_f32_16x16x32_bf16 v[64:67], v[152:155], v[212:215], v[64:67]
	v_mfma_f32_16x16x32_bf16 v[68:71], v[144:147], v[212:215], v[68:71]
	v_mfma_f32_16x16x32_bf16 v[72:75], v[136:139], v[212:215], v[72:75]
	v_mfma_f32_16x16x32_bf16 v[76:79], v[128:131], v[212:215], v[76:79]
	s_setprio 0
	s_barrier
	s_add_i32 s30, s36, s35
	s_mov_b32 m0, s30
	ds_read_b128 v[182:185], v206 offset:49152
	ds_read_b128 v[186:189], v206 offset:50176
	ds_read_b128 v[190:193], v206 offset:51200
	ds_read_b128 v[194:197], v206 offset:52224
	ds_read_b128 v[198:201], v206 offset:53248
	ds_read_b128 v[208:211], v206 offset:54272
	ds_read_b128 v[212:215], v206 offset:55296
	ds_read_b128 v[228:231], v206 offset:56320
	global_load_lds_dwordx4 v168, s[98:99]
	s_add_i32 m0, s30, 0x2000
	s_add_u32 s26, s26, 0x40080
	s_addc_u32 s27, s27, 0
	s_add_i32 s30, s37, s35
	global_load_lds_dwordx4 v160, s[98:99]
	s_mov_b32 m0, s30
	s_nop 0
	global_load_lds_dwordx4 v168, s[26:27]
	s_add_i32 m0, s30, 0x2000
	s_nop 0
	global_load_lds_dwordx4 v160, s[26:27]
	s_mov_b32 m0, s47
	s_nop 0
	global_load_lds_dwordx4 v164, s[100:101]
	s_mov_b32 m0, s48
	s_nop 0
	global_load_lds_dwordx4 v162, s[100:101]
	s_waitcnt vmcnt(8)
	s_waitcnt lgkmcnt(0)
	s_barrier
	s_setprio 1
	s_waitcnt lgkmcnt(0)
	v_mfma_f32_16x16x32_bf16 v[60:63], v[128:131], v[182:185], v[60:63]
	v_mfma_f32_16x16x32_bf16 v[56:59], v[136:139], v[182:185], v[56:59]
	v_mfma_f32_16x16x32_bf16 v[52:55], v[144:147], v[182:185], v[52:55]
	v_mfma_f32_16x16x32_bf16 v[48:51], v[152:155], v[182:185], v[48:51]
	v_mfma_f32_16x16x32_bf16 v[48:51], v[156:159], v[186:189], v[48:51]
	v_mfma_f32_16x16x32_bf16 v[52:55], v[148:151], v[186:189], v[52:55]
	v_mfma_f32_16x16x32_bf16 v[56:59], v[140:143], v[186:189], v[56:59]
	v_mfma_f32_16x16x32_bf16 v[60:63], v[132:135], v[186:189], v[60:63]
	v_mfma_f32_16x16x32_bf16 v[44:47], v[132:135], v[194:197], v[44:47]
	v_mfma_f32_16x16x32_bf16 v[40:43], v[140:143], v[194:197], v[40:43]
	v_mfma_f32_16x16x32_bf16 v[36:39], v[148:151], v[194:197], v[36:39]
	v_mfma_f32_16x16x32_bf16 v[32:35], v[156:159], v[194:197], v[32:35]
	v_mfma_f32_16x16x32_bf16 v[32:35], v[152:155], v[190:193], v[32:35]
	v_mfma_f32_16x16x32_bf16 v[36:39], v[144:147], v[190:193], v[36:39]
	v_mfma_f32_16x16x32_bf16 v[40:43], v[136:139], v[190:193], v[40:43]
	v_mfma_f32_16x16x32_bf16 v[44:47], v[128:131], v[190:193], v[44:47]
	v_mfma_f32_16x16x32_bf16 v[28:31], v[128:131], v[198:201], v[28:31]
	v_mfma_f32_16x16x32_bf16 v[24:27], v[136:139], v[198:201], v[24:27]
	v_mfma_f32_16x16x32_bf16 v[20:23], v[144:147], v[198:201], v[20:23]
	v_mfma_f32_16x16x32_bf16 v[16:19], v[152:155], v[198:201], v[16:19]
	v_mfma_f32_16x16x32_bf16 v[16:19], v[156:159], v[208:211], v[16:19]
	v_mfma_f32_16x16x32_bf16 v[20:23], v[148:151], v[208:211], v[20:23]
	v_mfma_f32_16x16x32_bf16 v[24:27], v[140:143], v[208:211], v[24:27]
	v_mfma_f32_16x16x32_bf16 v[28:31], v[132:135], v[208:211], v[28:31]
	v_mfma_f32_16x16x32_bf16 v[12:15], v[132:135], v[228:231], v[12:15]
	v_mfma_f32_16x16x32_bf16 v[8:11], v[140:143], v[228:231], v[8:11]
	v_mfma_f32_16x16x32_bf16 v[4:7], v[148:151], v[228:231], v[4:7]
	v_mfma_f32_16x16x32_bf16 v[0:3], v[156:159], v[228:231], v[0:3]
	v_mfma_f32_16x16x32_bf16 v[0:3], v[152:155], v[212:215], v[0:3]
	v_mfma_f32_16x16x32_bf16 v[4:7], v[144:147], v[212:215], v[4:7]
	v_mfma_f32_16x16x32_bf16 v[8:11], v[136:139], v[212:215], v[8:11]
	v_mfma_f32_16x16x32_bf16 v[12:15], v[128:131], v[212:215], v[12:15]
	s_setprio 0
	s_barrier
	s_add_i32 s55, s55, 2
	s_add_u32 s22, s22, 0x100
	s_addc_u32 s23, s23, 0
	s_add_u32 s53, s53, 0x100
	s_addc_u32 s54, s54, 0
	s_cmp_gt_u32 s55, 13
	s_cbranch_scc0 .LBB0_776
	s_and_b64 vcc, exec, s[10:11]
	s_cbranch_vccz .LBB0_779
	s_barrier

.LBB0_890:
	s_add_u32 s18, s0, 0xfffc0080
	s_addc_u32 s19, s1, -1
	s_add_i32 s36, 0, 0x10000
	s_cmp_eq_u32 s50, 12
	s_cselect_b32 s23, s13, s19
	s_cselect_b32 s22, s46, s18
	s_cselect_b32 s19, s11, s49
	s_cselect_b32 s18, s47, s48
	s_add_i32 s51, 0, 0x14000
	v_add_u32_e32 v140, s36, v193
	v_add_u32_e32 v180, s51, v193
	ds_read_b128 v[128:131], v140
	ds_read_b128 v[132:135], v140 offset:1024
	ds_read_b128 v[136:139], v140 offset:2048
	ds_read_b128 v[140:143], v140 offset:3072
	ds_read_b128 v[144:147], v180
	ds_read_b128 v[148:151], v180 offset:1024
	ds_read_b128 v[164:167], v180 offset:2048
	ds_read_b128 v[180:183], v180 offset:3072
	s_add_i32 m0, s30, 0xc000
	ds_read_b128 v[184:187], v198
	ds_read_b128 v[188:191], v198 offset:1024
	ds_read_b128 v[200:203], v198 offset:2048
	ds_read_b128 v[204:207], v198 offset:3072
	ds_read_b128 v[208:211], v198 offset:4096
	ds_read_b128 v[212:215], v198 offset:5120
	ds_read_b128 v[228:231], v198 offset:6144
	ds_read_b128 v[232:235], v198 offset:7168
	global_load_lds_dwordx4 v160, s[0:1]
	s_add_i32 m0, s30, 0xe000
	s_nop 0
	global_load_lds_dwordx4 v162, s[0:1]
	s_waitcnt vmcnt(8)
	s_waitcnt lgkmcnt(0)
	s_barrier
	s_setprio 1
	s_waitcnt lgkmcnt(0)
	v_mfma_f32_16x16x32_bf16 v[124:127], v[128:131], v[184:187], v[124:127]
	v_mfma_f32_16x16x32_bf16 v[120:123], v[136:139], v[184:187], v[120:123]
	v_mfma_f32_16x16x32_bf16 v[116:119], v[144:147], v[184:187], v[116:119]
	v_mfma_f32_16x16x32_bf16 v[112:115], v[164:167], v[184:187], v[112:115]
	v_mfma_f32_16x16x32_bf16 v[112:115], v[180:183], v[188:191], v[112:115]
	v_mfma_f32_16x16x32_bf16 v[116:119], v[148:151], v[188:191], v[116:119]
	v_mfma_f32_16x16x32_bf16 v[120:123], v[140:143], v[188:191], v[120:123]
	v_mfma_f32_16x16x32_bf16 v[124:127], v[132:135], v[188:191], v[124:127]
	v_mfma_f32_16x16x32_bf16 v[108:111], v[132:135], v[204:207], v[108:111]
	v_mfma_f32_16x16x32_bf16 v[104:107], v[140:143], v[204:207], v[104:107]
	v_mfma_f32_16x16x32_bf16 v[100:103], v[148:151], v[204:207], v[100:103]
	v_mfma_f32_16x16x32_bf16 v[96:99], v[180:183], v[204:207], v[96:99]
	v_mfma_f32_16x16x32_bf16 v[96:99], v[164:167], v[200:203], v[96:99]
	v_mfma_f32_16x16x32_bf16 v[100:103], v[144:147], v[200:203], v[100:103]
	v_mfma_f32_16x16x32_bf16 v[104:107], v[136:139], v[200:203], v[104:107]
	v_mfma_f32_16x16x32_bf16 v[108:111], v[128:131], v[200:203], v[108:111]
	v_mfma_f32_16x16x32_bf16 v[92:95], v[128:131], v[208:211], v[92:95]
	v_mfma_f32_16x16x32_bf16 v[88:91], v[136:139], v[208:211], v[88:91]
	v_mfma_f32_16x16x32_bf16 v[84:87], v[144:147], v[208:211], v[84:87]
	v_mfma_f32_16x16x32_bf16 v[80:83], v[164:167], v[208:211], v[80:83]
	v_mfma_f32_16x16x32_bf16 v[80:83], v[180:183], v[212:215], v[80:83]
	v_mfma_f32_16x16x32_bf16 v[84:87], v[148:151], v[212:215], v[84:87]
	v_mfma_f32_16x16x32_bf16 v[88:91], v[140:143], v[212:215], v[88:91]
	v_mfma_f32_16x16x32_bf16 v[92:95], v[132:135], v[212:215], v[92:95]
	v_mfma_f32_16x16x32_bf16 v[76:79], v[132:135], v[232:235], v[76:79]
	v_mfma_f32_16x16x32_bf16 v[72:75], v[140:143], v[232:235], v[72:75]
	v_mfma_f32_16x16x32_bf16 v[68:71], v[148:151], v[232:235], v[68:71]
	v_mfma_f32_16x16x32_bf16 v[64:67], v[180:183], v[232:235], v[64:67]
	v_mfma_f32_16x16x32_bf16 v[64:67], v[164:167], v[228:231], v[64:67]
	v_mfma_f32_16x16x32_bf16 v[68:71], v[144:147], v[228:231], v[68:71]
	v_mfma_f32_16x16x32_bf16 v[72:75], v[136:139], v[228:231], v[72:75]
	v_mfma_f32_16x16x32_bf16 v[76:79], v[128:131], v[228:231], v[76:79]
	s_setprio 0
	s_barrier
	s_add_i32 s36, s36, s27
	s_add_u32 s98, s18, s20
	s_addc_u32 s99, s19, s21
	s_mov_b32 m0, s36
	ds_read_b128 v[184:187], v198 offset:16384
	ds_read_b128 v[188:191], v198 offset:17408
	ds_read_b128 v[200:203], v198 offset:18432
	ds_read_b128 v[204:207], v198 offset:19456
	ds_read_b128 v[208:211], v198 offset:20480
	ds_read_b128 v[212:215], v198 offset:21504
	ds_read_b128 v[228:231], v198 offset:22528
	ds_read_b128 v[232:235], v198 offset:23552
	global_load_lds_dwordx4 v168, s[18:19]
	s_add_i32 m0, s36, 0x2000
	s_add_u32 s36, s18, 0x40000
	s_addc_u32 s37, s19, 0
	s_add_i32 s51, s51, s27
	global_load_lds_dwordx4 v152, s[18:19]
	s_mov_b32 m0, s51
	s_nop 0
	global_load_lds_dwordx4 v168, s[36:37]
	s_add_i32 m0, s51, 0x2000
	s_nop 0
	global_load_lds_dwordx4 v152, s[36:37]
	s_add_u32 s100, s22, s20
	s_addc_u32 s101, s23, s21
	s_mov_b32 m0, s30
	s_nop 0
	global_load_lds_dwordx4 v156, s[22:23]
	s_mov_b32 m0, s31
	s_nop 0
	global_load_lds_dwordx4 v154, s[22:23]
	s_waitcnt vmcnt(8)
	s_waitcnt lgkmcnt(0)
	s_barrier
	s_setprio 1
	s_waitcnt lgkmcnt(0)
	v_mfma_f32_16x16x32_bf16 v[60:63], v[128:131], v[184:187], v[60:63]
	v_mfma_f32_16x16x32_bf16 v[56:59], v[136:139], v[184:187], v[56:59]
	v_mfma_f32_16x16x32_bf16 v[52:55], v[144:147], v[184:187], v[52:55]
	v_mfma_f32_16x16x32_bf16 v[48:51], v[164:167], v[184:187], v[48:51]
	v_mfma_f32_16x16x32_bf16 v[48:51], v[180:183], v[188:191], v[48:51]
	v_mfma_f32_16x16x32_bf16 v[52:55], v[148:151], v[188:191], v[52:55]
	v_mfma_f32_16x16x32_bf16 v[56:59], v[140:143], v[188:191], v[56:59]
	v_mfma_f32_16x16x32_bf16 v[60:63], v[132:135], v[188:191], v[60:63]
	v_mfma_f32_16x16x32_bf16 v[44:47], v[132:135], v[204:207], v[44:47]
	v_mfma_f32_16x16x32_bf16 v[40:43], v[140:143], v[204:207], v[40:43]
	v_mfma_f32_16x16x32_bf16 v[36:39], v[148:151], v[204:207], v[36:39]
	v_mfma_f32_16x16x32_bf16 v[32:35], v[180:183], v[204:207], v[32:35]
	v_mfma_f32_16x16x32_bf16 v[32:35], v[164:167], v[200:203], v[32:35]
	v_mfma_f32_16x16x32_bf16 v[36:39], v[144:147], v[200:203], v[36:39]
	v_mfma_f32_16x16x32_bf16 v[40:43], v[136:139], v[200:203], v[40:43]
	v_mfma_f32_16x16x32_bf16 v[44:47], v[128:131], v[200:203], v[44:47]
	v_mfma_f32_16x16x32_bf16 v[28:31], v[128:131], v[208:211], v[28:31]
	v_mfma_f32_16x16x32_bf16 v[24:27], v[136:139], v[208:211], v[24:27]
	v_mfma_f32_16x16x32_bf16 v[20:23], v[144:147], v[208:211], v[20:23]
	v_mfma_f32_16x16x32_bf16 v[16:19], v[164:167], v[208:211], v[16:19]
	v_mfma_f32_16x16x32_bf16 v[16:19], v[180:183], v[212:215], v[16:19]
	v_mfma_f32_16x16x32_bf16 v[20:23], v[148:151], v[212:215], v[20:23]
	v_mfma_f32_16x16x32_bf16 v[24:27], v[140:143], v[212:215], v[24:27]
	v_mfma_f32_16x16x32_bf16 v[28:31], v[132:135], v[212:215], v[28:31]
	v_mfma_f32_16x16x32_bf16 v[12:15], v[132:135], v[232:235], v[12:15]
	v_mfma_f32_16x16x32_bf16 v[8:11], v[140:143], v[232:235], v[8:11]
	v_mfma_f32_16x16x32_bf16 v[4:7], v[148:151], v[232:235], v[4:7]
	v_mfma_f32_16x16x32_bf16 v[0:3], v[180:183], v[232:235], v[0:3]
	v_mfma_f32_16x16x32_bf16 v[0:3], v[164:167], v[228:231], v[0:3]
	v_mfma_f32_16x16x32_bf16 v[4:7], v[144:147], v[228:231], v[4:7]
	v_mfma_f32_16x16x32_bf16 v[8:11], v[136:139], v[228:231], v[8:11]
	v_mfma_f32_16x16x32_bf16 v[12:15], v[128:131], v[228:231], v[12:15]
	s_setprio 0
	s_barrier
	s_add_i32 s36, 0, 0x18000
	s_add_i32 s37, 0, 0x1c000
	v_add_u32_e32 v140, s36, v193
	v_add_u32_e32 v180, s37, v193
	ds_read_b128 v[128:131], v140
	ds_read_b128 v[132:135], v140 offset:1024
	ds_read_b128 v[136:139], v140 offset:2048
	ds_read_b128 v[140:143], v140 offset:3072
	ds_read_b128 v[144:147], v180
	ds_read_b128 v[148:151], v180 offset:1024
	ds_read_b128 v[164:167], v180 offset:2048
	ds_read_b128 v[180:183], v180 offset:3072
	s_add_u32 s22, s22, 0x40000
	s_addc_u32 s23, s23, 0
	s_mov_b32 m0, s34
	ds_read_b128 v[184:187], v198 offset:32768
	ds_read_b128 v[188:191], v198 offset:33792
	ds_read_b128 v[200:203], v198 offset:34816
	ds_read_b128 v[204:207], v198 offset:35840
	ds_read_b128 v[208:211], v198 offset:36864
	ds_read_b128 v[212:215], v198 offset:37888
	ds_read_b128 v[228:231], v198 offset:38912
	ds_read_b128 v[232:235], v198 offset:39936
	global_load_lds_dwordx4 v156, s[22:23]
	s_mov_b32 m0, s35
	s_nop 0
	global_load_lds_dwordx4 v154, s[22:23]
	s_waitcnt vmcnt(8)
	s_waitcnt lgkmcnt(0)
	s_barrier
	s_setprio 1
	s_waitcnt lgkmcnt(0)
	v_mfma_f32_16x16x32_bf16 v[124:127], v[128:131], v[184:187], v[124:127]
	v_mfma_f32_16x16x32_bf16 v[120:123], v[136:139], v[184:187], v[120:123]
	v_mfma_f32_16x16x32_bf16 v[116:119], v[144:147], v[184:187], v[116:119]
	v_mfma_f32_16x16x32_bf16 v[112:115], v[164:167], v[184:187], v[112:115]
	v_mfma_f32_16x16x32_bf16 v[112:115], v[180:183], v[188:191], v[112:115]
	v_mfma_f32_16x16x32_bf16 v[116:119], v[148:151], v[188:191], v[116:119]
	v_mfma_f32_16x16x32_bf16 v[120:123], v[140:143], v[188:191], v[120:123]
	v_mfma_f32_16x16x32_bf16 v[124:127], v[132:135], v[188:191], v[124:127]
	v_mfma_f32_16x16x32_bf16 v[108:111], v[132:135], v[204:207], v[108:111]
	v_mfma_f32_16x16x32_bf16 v[104:107], v[140:143], v[204:207], v[104:107]
	v_mfma_f32_16x16x32_bf16 v[100:103], v[148:151], v[204:207], v[100:103]
	v_mfma_f32_16x16x32_bf16 v[96:99], v[180:183], v[204:207], v[96:99]
	v_mfma_f32_16x16x32_bf16 v[96:99], v[164:167], v[200:203], v[96:99]
	v_mfma_f32_16x16x32_bf16 v[100:103], v[144:147], v[200:203], v[100:103]
	v_mfma_f32_16x16x32_bf16 v[104:107], v[136:139], v[200:203], v[104:107]
	v_mfma_f32_16x16x32_bf16 v[108:111], v[128:131], v[200:203], v[108:111]
	v_mfma_f32_16x16x32_bf16 v[92:95], v[128:131], v[208:211], v[92:95]
	v_mfma_f32_16x16x32_bf16 v[88:91], v[136:139], v[208:211], v[88:91]
	v_mfma_f32_16x16x32_bf16 v[84:87], v[144:147], v[208:211], v[84:87]
	v_mfma_f32_16x16x32_bf16 v[80:83], v[164:167], v[208:211], v[80:83]
	v_mfma_f32_16x16x32_bf16 v[80:83], v[180:183], v[212:215], v[80:83]
	v_mfma_f32_16x16x32_bf16 v[84:87], v[148:151], v[212:215], v[84:87]
	v_mfma_f32_16x16x32_bf16 v[88:91], v[140:143], v[212:215], v[88:91]
	v_mfma_f32_16x16x32_bf16 v[92:95], v[132:135], v[212:215], v[92:95]
	v_mfma_f32_16x16x32_bf16 v[76:79], v[132:135], v[232:235], v[76:79]
	v_mfma_f32_16x16x32_bf16 v[72:75], v[140:143], v[232:235], v[72:75]
	v_mfma_f32_16x16x32_bf16 v[68:71], v[148:151], v[232:235], v[68:71]
	v_mfma_f32_16x16x32_bf16 v[64:67], v[180:183], v[232:235], v[64:67]
	v_mfma_f32_16x16x32_bf16 v[64:67], v[164:167], v[228:231], v[64:67]
	v_mfma_f32_16x16x32_bf16 v[68:71], v[144:147], v[228:231], v[68:71]
	v_mfma_f32_16x16x32_bf16 v[72:75], v[136:139], v[228:231], v[72:75]
	v_mfma_f32_16x16x32_bf16 v[76:79], v[128:131], v[228:231], v[76:79]
	s_setprio 0
	s_barrier
	s_add_i32 s22, s36, s27
	s_mov_b32 m0, s22
	ds_read_b128 v[184:187], v198 offset:49152
	ds_read_b128 v[188:191], v198 offset:50176
	ds_read_b128 v[200:203], v198 offset:51200
	ds_read_b128 v[204:207], v198 offset:52224
	ds_read_b128 v[208:211], v198 offset:53248
	ds_read_b128 v[212:215], v198 offset:54272
	ds_read_b128 v[228:231], v198 offset:55296
	ds_read_b128 v[232:235], v198 offset:56320
	global_load_lds_dwordx4 v168, s[98:99]
	s_add_i32 m0, s22, 0x2000
	s_add_u32 s18, s18, 0x40080
	s_addc_u32 s19, s19, 0
	s_add_i32 s22, s37, s27
	global_load_lds_dwordx4 v152, s[98:99]
	s_mov_b32 m0, s22
	s_nop 0
	global_load_lds_dwordx4 v168, s[18:19]
	s_add_i32 m0, s22, 0x2000
	s_nop 0
	global_load_lds_dwordx4 v152, s[18:19]
	s_mov_b32 m0, s24
	s_nop 0
	global_load_lds_dwordx4 v156, s[100:101]
	s_mov_b32 m0, s42
	s_nop 0
	global_load_lds_dwordx4 v154, s[100:101]
	s_waitcnt vmcnt(8)
	s_waitcnt lgkmcnt(0)
	s_barrier
	s_setprio 1
	s_waitcnt lgkmcnt(0)
	v_mfma_f32_16x16x32_bf16 v[60:63], v[128:131], v[184:187], v[60:63]
	v_mfma_f32_16x16x32_bf16 v[56:59], v[136:139], v[184:187], v[56:59]
	v_mfma_f32_16x16x32_bf16 v[52:55], v[144:147], v[184:187], v[52:55]
	v_mfma_f32_16x16x32_bf16 v[48:51], v[164:167], v[184:187], v[48:51]
	v_mfma_f32_16x16x32_bf16 v[48:51], v[180:183], v[188:191], v[48:51]
	v_mfma_f32_16x16x32_bf16 v[52:55], v[148:151], v[188:191], v[52:55]
	v_mfma_f32_16x16x32_bf16 v[56:59], v[140:143], v[188:191], v[56:59]
	v_mfma_f32_16x16x32_bf16 v[60:63], v[132:135], v[188:191], v[60:63]
	v_mfma_f32_16x16x32_bf16 v[44:47], v[132:135], v[204:207], v[44:47]
	v_mfma_f32_16x16x32_bf16 v[40:43], v[140:143], v[204:207], v[40:43]
	v_mfma_f32_16x16x32_bf16 v[36:39], v[148:151], v[204:207], v[36:39]
	v_mfma_f32_16x16x32_bf16 v[32:35], v[180:183], v[204:207], v[32:35]
	v_mfma_f32_16x16x32_bf16 v[32:35], v[164:167], v[200:203], v[32:35]
	v_mfma_f32_16x16x32_bf16 v[36:39], v[144:147], v[200:203], v[36:39]
	v_mfma_f32_16x16x32_bf16 v[40:43], v[136:139], v[200:203], v[40:43]
	v_mfma_f32_16x16x32_bf16 v[44:47], v[128:131], v[200:203], v[44:47]
	v_mfma_f32_16x16x32_bf16 v[28:31], v[128:131], v[208:211], v[28:31]
	v_mfma_f32_16x16x32_bf16 v[24:27], v[136:139], v[208:211], v[24:27]
	v_mfma_f32_16x16x32_bf16 v[20:23], v[144:147], v[208:211], v[20:23]
	v_mfma_f32_16x16x32_bf16 v[16:19], v[164:167], v[208:211], v[16:19]
	v_mfma_f32_16x16x32_bf16 v[16:19], v[180:183], v[212:215], v[16:19]
	v_mfma_f32_16x16x32_bf16 v[20:23], v[148:151], v[212:215], v[20:23]
	v_mfma_f32_16x16x32_bf16 v[24:27], v[140:143], v[212:215], v[24:27]
	v_mfma_f32_16x16x32_bf16 v[28:31], v[132:135], v[212:215], v[28:31]
	v_mfma_f32_16x16x32_bf16 v[12:15], v[132:135], v[232:235], v[12:15]
	v_mfma_f32_16x16x32_bf16 v[8:11], v[140:143], v[232:235], v[8:11]
	v_mfma_f32_16x16x32_bf16 v[4:7], v[148:151], v[232:235], v[4:7]
	v_mfma_f32_16x16x32_bf16 v[0:3], v[180:183], v[232:235], v[0:3]
	v_mfma_f32_16x16x32_bf16 v[0:3], v[164:167], v[228:231], v[0:3]
	v_mfma_f32_16x16x32_bf16 v[4:7], v[144:147], v[228:231], v[4:7]
	v_mfma_f32_16x16x32_bf16 v[8:11], v[136:139], v[228:231], v[8:11]
	v_mfma_f32_16x16x32_bf16 v[12:15], v[128:131], v[228:231], v[12:15]
	s_setprio 0
	s_barrier
	s_add_i32 s50, s50, 2
	s_add_u32 s0, s0, 0x100
	s_addc_u32 s1, s1, 0
	s_add_u32 s48, s48, 0x100
	s_addc_u32 s49, s49, 0
	s_cmp_gt_u32 s50, 13
	s_cbranch_scc0 .LBB0_890
	s_and_b64 vcc, exec, s[8:9]
	s_cbranch_vccz .LBB0_893
	s_barrier

.LBB0_986:
	s_add_u32 s34, s8, 0xfff00080
	s_addc_u32 s35, s9, -1
	s_add_i32 s36, 0, 0x10000
	s_cmp_eq_u32 s57, 60
	s_cselect_b32 s41, s23, s35
	s_cselect_b32 s40, s53, s34
	s_cselect_b32 s35, s19, s56
	s_cselect_b32 s34, s54, s55
	s_add_i32 s58, 0, 0x14000
	v_add_u32_e32 v140, s36, v228
	v_add_u32_e32 v156, s58, v228
	ds_read_b128 v[128:131], v140
	ds_read_b128 v[132:135], v140 offset:1024
	ds_read_b128 v[136:139], v140 offset:2048
	ds_read_b128 v[140:143], v140 offset:3072
	ds_read_b128 v[144:147], v156
	ds_read_b128 v[148:151], v156 offset:1024
	ds_read_b128 v[152:155], v156 offset:2048
	ds_read_b128 v[156:159], v156 offset:3072
	s_add_i32 m0, s44, 0xc000
	ds_read_b128 v[160:163], v230
	ds_read_b128 v[164:167], v230 offset:1024
	ds_read_b128 v[190:193], v230 offset:2048
	ds_read_b128 v[194:197], v230 offset:3072
	ds_read_b128 v[198:201], v230 offset:4096
	ds_read_b128 v[202:205], v230 offset:5120
	ds_read_b128 v[206:209], v230 offset:6144
	ds_read_b128 v[210:213], v230 offset:7168
	global_load_lds_dwordx4 v186, s[8:9]
	s_add_i32 m0, s44, 0xe000
	s_nop 0
	global_load_lds_dwordx4 v188, s[8:9]
	s_waitcnt vmcnt(8)
	s_waitcnt lgkmcnt(0)
	s_barrier
	s_setprio 1
	s_waitcnt lgkmcnt(0)
	v_mfma_f32_16x16x32_bf16 v[124:127], v[128:131], v[160:163], v[124:127]
	v_mfma_f32_16x16x32_bf16 v[120:123], v[136:139], v[160:163], v[120:123]
	v_mfma_f32_16x16x32_bf16 v[116:119], v[144:147], v[160:163], v[116:119]
	v_mfma_f32_16x16x32_bf16 v[112:115], v[152:155], v[160:163], v[112:115]
	v_mfma_f32_16x16x32_bf16 v[112:115], v[156:159], v[164:167], v[112:115]
	v_mfma_f32_16x16x32_bf16 v[116:119], v[148:151], v[164:167], v[116:119]
	v_mfma_f32_16x16x32_bf16 v[120:123], v[140:143], v[164:167], v[120:123]
	v_mfma_f32_16x16x32_bf16 v[124:127], v[132:135], v[164:167], v[124:127]
	v_mfma_f32_16x16x32_bf16 v[108:111], v[132:135], v[194:197], v[108:111]
	v_mfma_f32_16x16x32_bf16 v[104:107], v[140:143], v[194:197], v[104:107]
	v_mfma_f32_16x16x32_bf16 v[100:103], v[148:151], v[194:197], v[100:103]
	v_mfma_f32_16x16x32_bf16 v[96:99], v[156:159], v[194:197], v[96:99]
	v_mfma_f32_16x16x32_bf16 v[96:99], v[152:155], v[190:193], v[96:99]
	v_mfma_f32_16x16x32_bf16 v[100:103], v[144:147], v[190:193], v[100:103]
	v_mfma_f32_16x16x32_bf16 v[104:107], v[136:139], v[190:193], v[104:107]
	v_mfma_f32_16x16x32_bf16 v[108:111], v[128:131], v[190:193], v[108:111]
	v_mfma_f32_16x16x32_bf16 v[92:95], v[128:131], v[198:201], v[92:95]
	v_mfma_f32_16x16x32_bf16 v[88:91], v[136:139], v[198:201], v[88:91]
	v_mfma_f32_16x16x32_bf16 v[84:87], v[144:147], v[198:201], v[84:87]
	v_mfma_f32_16x16x32_bf16 v[80:83], v[152:155], v[198:201], v[80:83]
	v_mfma_f32_16x16x32_bf16 v[80:83], v[156:159], v[202:205], v[80:83]
	v_mfma_f32_16x16x32_bf16 v[84:87], v[148:151], v[202:205], v[84:87]
	v_mfma_f32_16x16x32_bf16 v[88:91], v[140:143], v[202:205], v[88:91]
	v_mfma_f32_16x16x32_bf16 v[92:95], v[132:135], v[202:205], v[92:95]
	v_mfma_f32_16x16x32_bf16 v[76:79], v[132:135], v[210:213], v[76:79]
	v_mfma_f32_16x16x32_bf16 v[72:75], v[140:143], v[210:213], v[72:75]
	v_mfma_f32_16x16x32_bf16 v[68:71], v[148:151], v[210:213], v[68:71]
	v_mfma_f32_16x16x32_bf16 v[64:67], v[156:159], v[210:213], v[64:67]
	v_mfma_f32_16x16x32_bf16 v[64:67], v[152:155], v[206:209], v[64:67]
	v_mfma_f32_16x16x32_bf16 v[68:71], v[144:147], v[206:209], v[68:71]
	v_mfma_f32_16x16x32_bf16 v[72:75], v[136:139], v[206:209], v[72:75]
	v_mfma_f32_16x16x32_bf16 v[76:79], v[128:131], v[206:209], v[76:79]
	s_setprio 0
	s_barrier
	s_add_i32 s36, s36, s43
	s_add_u32 s98, s34, s20
	s_addc_u32 s99, s35, s21
	s_mov_b32 m0, s36
	ds_read_b128 v[160:163], v230 offset:16384
	ds_read_b128 v[164:167], v230 offset:17408
	ds_read_b128 v[190:193], v230 offset:18432
	ds_read_b128 v[194:197], v230 offset:19456
	ds_read_b128 v[198:201], v230 offset:20480
	ds_read_b128 v[202:205], v230 offset:21504
	ds_read_b128 v[206:209], v230 offset:22528
	ds_read_b128 v[210:213], v230 offset:23552
	global_load_lds_dwordx4 v168, s[34:35]
	s_add_i32 m0, s36, 0x2000
	s_add_u32 s36, s34, 0x100000
	s_addc_u32 s37, s35, 0
	s_add_i32 s58, s58, s43
	global_load_lds_dwordx4 v180, s[34:35]
	s_mov_b32 m0, s58
	s_nop 0
	global_load_lds_dwordx4 v168, s[36:37]
	s_add_i32 m0, s58, 0x2000
	s_nop 0
	global_load_lds_dwordx4 v180, s[36:37]
	s_add_u32 s100, s40, s20
	s_addc_u32 s101, s41, s21
	s_mov_b32 m0, s44
	s_nop 0
	global_load_lds_dwordx4 v184, s[40:41]
	s_mov_b32 m0, s45
	s_nop 0
	global_load_lds_dwordx4 v182, s[40:41]
	s_waitcnt vmcnt(8)
	s_waitcnt lgkmcnt(0)
	s_barrier
	s_setprio 1
	s_waitcnt lgkmcnt(0)
	v_mfma_f32_16x16x32_bf16 v[60:63], v[128:131], v[160:163], v[60:63]
	v_mfma_f32_16x16x32_bf16 v[56:59], v[136:139], v[160:163], v[56:59]
	v_mfma_f32_16x16x32_bf16 v[52:55], v[144:147], v[160:163], v[52:55]
	v_mfma_f32_16x16x32_bf16 v[48:51], v[152:155], v[160:163], v[48:51]
	v_mfma_f32_16x16x32_bf16 v[48:51], v[156:159], v[164:167], v[48:51]
	v_mfma_f32_16x16x32_bf16 v[52:55], v[148:151], v[164:167], v[52:55]
	v_mfma_f32_16x16x32_bf16 v[56:59], v[140:143], v[164:167], v[56:59]
	v_mfma_f32_16x16x32_bf16 v[60:63], v[132:135], v[164:167], v[60:63]
	v_mfma_f32_16x16x32_bf16 v[44:47], v[132:135], v[194:197], v[44:47]
	v_mfma_f32_16x16x32_bf16 v[40:43], v[140:143], v[194:197], v[40:43]
	v_mfma_f32_16x16x32_bf16 v[36:39], v[148:151], v[194:197], v[36:39]
	v_mfma_f32_16x16x32_bf16 v[32:35], v[156:159], v[194:197], v[32:35]
	v_mfma_f32_16x16x32_bf16 v[32:35], v[152:155], v[190:193], v[32:35]
	v_mfma_f32_16x16x32_bf16 v[36:39], v[144:147], v[190:193], v[36:39]
	v_mfma_f32_16x16x32_bf16 v[40:43], v[136:139], v[190:193], v[40:43]
	v_mfma_f32_16x16x32_bf16 v[44:47], v[128:131], v[190:193], v[44:47]
	v_mfma_f32_16x16x32_bf16 v[28:31], v[128:131], v[198:201], v[28:31]
	v_mfma_f32_16x16x32_bf16 v[24:27], v[136:139], v[198:201], v[24:27]
	v_mfma_f32_16x16x32_bf16 v[20:23], v[144:147], v[198:201], v[20:23]
	v_mfma_f32_16x16x32_bf16 v[16:19], v[152:155], v[198:201], v[16:19]
	v_mfma_f32_16x16x32_bf16 v[16:19], v[156:159], v[202:205], v[16:19]
	v_mfma_f32_16x16x32_bf16 v[20:23], v[148:151], v[202:205], v[20:23]
	v_mfma_f32_16x16x32_bf16 v[24:27], v[140:143], v[202:205], v[24:27]
	v_mfma_f32_16x16x32_bf16 v[28:31], v[132:135], v[202:205], v[28:31]
	v_mfma_f32_16x16x32_bf16 v[12:15], v[132:135], v[210:213], v[12:15]
	v_mfma_f32_16x16x32_bf16 v[8:11], v[140:143], v[210:213], v[8:11]
	v_mfma_f32_16x16x32_bf16 v[4:7], v[148:151], v[210:213], v[4:7]
	v_mfma_f32_16x16x32_bf16 v[0:3], v[156:159], v[210:213], v[0:3]
	v_mfma_f32_16x16x32_bf16 v[0:3], v[152:155], v[206:209], v[0:3]
	v_mfma_f32_16x16x32_bf16 v[4:7], v[144:147], v[206:209], v[4:7]
	v_mfma_f32_16x16x32_bf16 v[8:11], v[136:139], v[206:209], v[8:11]
	v_mfma_f32_16x16x32_bf16 v[12:15], v[128:131], v[206:209], v[12:15]
	s_setprio 0
	s_barrier
	s_add_i32 s58, 0, 0x18000
	s_add_i32 s59, 0, 0x1c000
	v_add_u32_e32 v140, s58, v228
	v_add_u32_e32 v156, s59, v228
	ds_read_b128 v[128:131], v140
	ds_read_b128 v[132:135], v140 offset:1024
	ds_read_b128 v[136:139], v140 offset:2048
	ds_read_b128 v[140:143], v140 offset:3072
	ds_read_b128 v[144:147], v156
	ds_read_b128 v[148:151], v156 offset:1024
	ds_read_b128 v[152:155], v156 offset:2048
	ds_read_b128 v[156:159], v156 offset:3072
	s_add_u32 s36, s40, 0x100000
	s_addc_u32 s37, s41, 0
	s_mov_b32 m0, s46
	ds_read_b128 v[160:163], v230 offset:32768
	ds_read_b128 v[164:167], v230 offset:33792
	ds_read_b128 v[190:193], v230 offset:34816
	ds_read_b128 v[194:197], v230 offset:35840
	ds_read_b128 v[198:201], v230 offset:36864
	ds_read_b128 v[202:205], v230 offset:37888
	ds_read_b128 v[206:209], v230 offset:38912
	ds_read_b128 v[210:213], v230 offset:39936
	global_load_lds_dwordx4 v184, s[36:37]
	s_mov_b32 m0, s47
	s_nop 0
	global_load_lds_dwordx4 v182, s[36:37]
	s_waitcnt vmcnt(8)
	s_waitcnt lgkmcnt(0)
	s_barrier
	s_setprio 1
	s_waitcnt lgkmcnt(0)
	v_mfma_f32_16x16x32_bf16 v[124:127], v[128:131], v[160:163], v[124:127]
	v_mfma_f32_16x16x32_bf16 v[120:123], v[136:139], v[160:163], v[120:123]
	v_mfma_f32_16x16x32_bf16 v[116:119], v[144:147], v[160:163], v[116:119]
	v_mfma_f32_16x16x32_bf16 v[112:115], v[152:155], v[160:163], v[112:115]
	v_mfma_f32_16x16x32_bf16 v[112:115], v[156:159], v[164:167], v[112:115]
	v_mfma_f32_16x16x32_bf16 v[116:119], v[148:151], v[164:167], v[116:119]
	v_mfma_f32_16x16x32_bf16 v[120:123], v[140:143], v[164:167], v[120:123]
	v_mfma_f32_16x16x32_bf16 v[124:127], v[132:135], v[164:167], v[124:127]
	v_mfma_f32_16x16x32_bf16 v[108:111], v[132:135], v[194:197], v[108:111]
	v_mfma_f32_16x16x32_bf16 v[104:107], v[140:143], v[194:197], v[104:107]
	v_mfma_f32_16x16x32_bf16 v[100:103], v[148:151], v[194:197], v[100:103]
	v_mfma_f32_16x16x32_bf16 v[96:99], v[156:159], v[194:197], v[96:99]
	v_mfma_f32_16x16x32_bf16 v[96:99], v[152:155], v[190:193], v[96:99]
	v_mfma_f32_16x16x32_bf16 v[100:103], v[144:147], v[190:193], v[100:103]
	v_mfma_f32_16x16x32_bf16 v[104:107], v[136:139], v[190:193], v[104:107]
	v_mfma_f32_16x16x32_bf16 v[108:111], v[128:131], v[190:193], v[108:111]
	v_mfma_f32_16x16x32_bf16 v[92:95], v[128:131], v[198:201], v[92:95]
	v_mfma_f32_16x16x32_bf16 v[88:91], v[136:139], v[198:201], v[88:91]
	v_mfma_f32_16x16x32_bf16 v[84:87], v[144:147], v[198:201], v[84:87]
	v_mfma_f32_16x16x32_bf16 v[80:83], v[152:155], v[198:201], v[80:83]
	v_mfma_f32_16x16x32_bf16 v[80:83], v[156:159], v[202:205], v[80:83]
	v_mfma_f32_16x16x32_bf16 v[84:87], v[148:151], v[202:205], v[84:87]
	v_mfma_f32_16x16x32_bf16 v[88:91], v[140:143], v[202:205], v[88:91]
	v_mfma_f32_16x16x32_bf16 v[92:95], v[132:135], v[202:205], v[92:95]
	v_mfma_f32_16x16x32_bf16 v[76:79], v[132:135], v[210:213], v[76:79]
	v_mfma_f32_16x16x32_bf16 v[72:75], v[140:143], v[210:213], v[72:75]
	v_mfma_f32_16x16x32_bf16 v[68:71], v[148:151], v[210:213], v[68:71]
	v_mfma_f32_16x16x32_bf16 v[64:67], v[156:159], v[210:213], v[64:67]
	v_mfma_f32_16x16x32_bf16 v[64:67], v[152:155], v[206:209], v[64:67]
	v_mfma_f32_16x16x32_bf16 v[68:71], v[144:147], v[206:209], v[68:71]
	v_mfma_f32_16x16x32_bf16 v[72:75], v[136:139], v[206:209], v[72:75]
	v_mfma_f32_16x16x32_bf16 v[76:79], v[128:131], v[206:209], v[76:79]
	s_setprio 0
	s_barrier
	s_add_i32 s36, s58, s43
	s_mov_b32 m0, s36
	ds_read_b128 v[160:163], v230 offset:49152
	ds_read_b128 v[164:167], v230 offset:50176
	ds_read_b128 v[190:193], v230 offset:51200
	ds_read_b128 v[194:197], v230 offset:52224
	ds_read_b128 v[198:201], v230 offset:53248
	ds_read_b128 v[202:205], v230 offset:54272
	ds_read_b128 v[206:209], v230 offset:55296
	ds_read_b128 v[210:213], v230 offset:56320
	global_load_lds_dwordx4 v168, s[98:99]
	s_add_i32 m0, s36, 0x2000
	s_add_u32 s34, s34, 0x100080
	s_addc_u32 s35, s35, 0
	s_add_i32 s36, s59, s43
	global_load_lds_dwordx4 v180, s[98:99]
	s_mov_b32 m0, s36
	s_nop 0
	global_load_lds_dwordx4 v168, s[34:35]
	s_add_i32 m0, s36, 0x2000
	s_nop 0
	global_load_lds_dwordx4 v180, s[34:35]
	s_mov_b32 m0, s50
	s_nop 0
	global_load_lds_dwordx4 v184, s[100:101]
	s_mov_b32 m0, s51
	s_nop 0
	global_load_lds_dwordx4 v182, s[100:101]
	s_waitcnt vmcnt(8)
	s_waitcnt lgkmcnt(0)
	s_barrier
	s_setprio 1
	s_waitcnt lgkmcnt(0)
	v_mfma_f32_16x16x32_bf16 v[60:63], v[128:131], v[160:163], v[60:63]
	v_mfma_f32_16x16x32_bf16 v[56:59], v[136:139], v[160:163], v[56:59]
	v_mfma_f32_16x16x32_bf16 v[52:55], v[144:147], v[160:163], v[52:55]
	v_mfma_f32_16x16x32_bf16 v[48:51], v[152:155], v[160:163], v[48:51]
	v_mfma_f32_16x16x32_bf16 v[48:51], v[156:159], v[164:167], v[48:51]
	v_mfma_f32_16x16x32_bf16 v[52:55], v[148:151], v[164:167], v[52:55]
	v_mfma_f32_16x16x32_bf16 v[56:59], v[140:143], v[164:167], v[56:59]
	v_mfma_f32_16x16x32_bf16 v[60:63], v[132:135], v[164:167], v[60:63]
	v_mfma_f32_16x16x32_bf16 v[44:47], v[132:135], v[194:197], v[44:47]
	v_mfma_f32_16x16x32_bf16 v[40:43], v[140:143], v[194:197], v[40:43]
	v_mfma_f32_16x16x32_bf16 v[36:39], v[148:151], v[194:197], v[36:39]
	v_mfma_f32_16x16x32_bf16 v[32:35], v[156:159], v[194:197], v[32:35]
	v_mfma_f32_16x16x32_bf16 v[32:35], v[152:155], v[190:193], v[32:35]
	v_mfma_f32_16x16x32_bf16 v[36:39], v[144:147], v[190:193], v[36:39]
	v_mfma_f32_16x16x32_bf16 v[40:43], v[136:139], v[190:193], v[40:43]
	v_mfma_f32_16x16x32_bf16 v[44:47], v[128:131], v[190:193], v[44:47]
	v_mfma_f32_16x16x32_bf16 v[28:31], v[128:131], v[198:201], v[28:31]
	v_mfma_f32_16x16x32_bf16 v[24:27], v[136:139], v[198:201], v[24:27]
	v_mfma_f32_16x16x32_bf16 v[20:23], v[144:147], v[198:201], v[20:23]
	v_mfma_f32_16x16x32_bf16 v[16:19], v[152:155], v[198:201], v[16:19]
	v_mfma_f32_16x16x32_bf16 v[16:19], v[156:159], v[202:205], v[16:19]
	v_mfma_f32_16x16x32_bf16 v[20:23], v[148:151], v[202:205], v[20:23]
	v_mfma_f32_16x16x32_bf16 v[24:27], v[140:143], v[202:205], v[24:27]
	v_mfma_f32_16x16x32_bf16 v[28:31], v[132:135], v[202:205], v[28:31]
	v_mfma_f32_16x16x32_bf16 v[12:15], v[132:135], v[210:213], v[12:15]
	v_mfma_f32_16x16x32_bf16 v[8:11], v[140:143], v[210:213], v[8:11]
	v_mfma_f32_16x16x32_bf16 v[4:7], v[148:151], v[210:213], v[4:7]
	v_mfma_f32_16x16x32_bf16 v[0:3], v[156:159], v[210:213], v[0:3]
	v_mfma_f32_16x16x32_bf16 v[0:3], v[152:155], v[206:209], v[0:3]
	v_mfma_f32_16x16x32_bf16 v[4:7], v[144:147], v[206:209], v[4:7]
	v_mfma_f32_16x16x32_bf16 v[8:11], v[136:139], v[206:209], v[8:11]
	v_mfma_f32_16x16x32_bf16 v[12:15], v[128:131], v[206:209], v[12:15]
	s_setprio 0
	s_barrier
	s_add_i32 s57, s57, 2
	s_add_u32 s8, s8, 0x100
	s_addc_u32 s9, s9, 0
	s_add_u32 s55, s55, 0x100
	s_addc_u32 s56, s56, 0
	s_cmp_gt_u32 s57, 61
	s_cbranch_scc0 .LBB0_986
	s_and_b64 vcc, exec, s[12:13]
	s_cbranch_vccz .LBB0_989
	s_barrier
